# speedup vs baseline: 1.0080x; 1.0033x over previous
_Z11mega_kernel1P:
	s_bitcmp0_b32 s2, 3
	s_cbranch_scc1 .LBB0_prio_done
	s_setprio 1
